# P0 rows loop: the eight lane-xor-32 exchanges of the transpose-reduce via v_permlane32_swap instead of select + ds_bpermute + select
# speedup vs baseline: 1.0032x; 1.0013x over previous
.Lp0rows_nopf:
	s_waitcnt lgkmcnt(1)
	v_fmac_f32_e32 v23, v230, v0
	v_fma_f32 v29, v232, v72, 0
	v_fma_f32 v62, v224, v188, 0
	v_fma_f32 v55, v232, v192, 0
	v_fmac_f32_e32 v52, v226, v18
	v_fmac_f32_e32 v40, v227, v11
	v_fmac_f32_e32 v32, v235, v15
	v_fmac_f32_e32 v54, v226, v154
	v_fmac_f32_e32 v61, v234, v158
	v_fmac_f32_e32 v53, v227, v139
	v_fmac_f32_e32 v35, v235, v143
	v_add_f32_e32 v16, v34, v43
	v_fmac_f32_e32 v23, v231, v1
	v_fmac_f32_e32 v29, v233, v73
	v_fma_f32 v25, v224, v80, 0
	v_fma_f32 v30, v232, v84, 0
	v_fmac_f32_e32 v62, v225, v189
	v_fmac_f32_e32 v55, v233, v193
	v_fma_f32 v63, v224, v200, 0
	v_fma_f32 v65, v232, v246, 0
	v_fmac_f32_e32 v52, v227, v19
	v_add_f32_e32 v9, v40, v32
	v_fmac_f32_e32 v54, v227, v155
	v_fmac_f32_e32 v61, v235, v159
	v_add_f32_e32 v17, v53, v35
	v_fmac_f32_e32 v23, v226, v2
	s_nop 1
	v_permlane32_swap_b32_e32 v8, v16
	v_fma_f32 v31, v224, v92, 0
	v_fma_f32 v26, v232, v100, 0
	v_fmac_f32_e32 v29, v228, v74
	v_fmac_f32_e32 v25, v225, v81
	v_fmac_f32_e32 v30, v233, v85
	v_fmac_f32_e32 v62, v222, v190
	v_fmac_f32_e32 v55, v228, v194
	v_fmac_f32_e32 v63, v225, v201
	v_fmac_f32_e32 v65, v233, v247
	v_add_f32_e32 v10, v52, v60
	v_add_f32_e32 v18, v54, v61
	v_fmac_f32_e32 v23, v227, v3
	s_nop 1
	v_permlane32_swap_b32_e32 v9, v17
	v_fmac_f32_e32 v31, v225, v93
	v_fmac_f32_e32 v26, v233, v101
	v_fmac_f32_e32 v64, v223, v67
	v_fmac_f32_e32 v29, v229, v75
	v_fmac_f32_e32 v25, v222, v82
	v_fmac_f32_e32 v30, v228, v86
	v_fmac_f32_e32 v62, v223, v191
	v_fmac_f32_e32 v55, v229, v195
	v_fmac_f32_e32 v63, v222, v202
	v_fmac_f32_e32 v65, v228, v248
	s_waitcnt lgkmcnt(0)
	v_fmac_f32_e32 v24, v236, v4
	s_nop 1
	v_permlane32_swap_b32_e32 v10, v18
	v_fmac_f32_e32 v31, v222, v94
	v_fmac_f32_e32 v26, v228, v102
	v_fmac_f32_e32 v64, v230, v36
	v_fmac_f32_e32 v29, v236, v44
	v_fmac_f32_e32 v25, v223, v83
	v_fmac_f32_e32 v30, v229, v87
	v_fmac_f32_e32 v62, v230, v172
	v_fmac_f32_e32 v55, v236, v180
	v_fmac_f32_e32 v63, v223, v203
	v_fmac_f32_e32 v65, v229, v249
	v_fmac_f32_e32 v31, v223, v95
	v_fmac_f32_e32 v26, v229, v103
	v_fmac_f32_e32 v64, v231, v37
	v_fmac_f32_e32 v29, v237, v45
	v_fmac_f32_e32 v25, v230, v48
	v_fmac_f32_e32 v30, v236, v56
	v_fmac_f32_e32 v62, v231, v173
	v_fmac_f32_e32 v55, v237, v181
	v_fmac_f32_e32 v63, v230, v196
	v_fmac_f32_e32 v65, v236, v204
	v_fmac_f32_e32 v31, v230, v68
	v_fmac_f32_e32 v26, v236, v76
	v_fmac_f32_e32 v64, v226, v38
	v_fmac_f32_e32 v29, v234, v46
	v_fmac_f32_e32 v25, v231, v49
	v_fmac_f32_e32 v30, v237, v57
	v_fmac_f32_e32 v62, v226, v174
	v_fmac_f32_e32 v55, v234, v182
	v_fmac_f32_e32 v63, v231, v197
	v_fmac_f32_e32 v65, v237, v205
	v_fmac_f32_e32 v31, v231, v69
	v_fmac_f32_e32 v26, v237, v77
	v_fmac_f32_e32 v64, v227, v39
	v_fmac_f32_e32 v29, v235, v47
	v_fmac_f32_e32 v25, v226, v50
	v_fmac_f32_e32 v30, v234, v58
	v_fmac_f32_e32 v62, v227, v175
	v_fmac_f32_e32 v55, v235, v183
	v_fmac_f32_e32 v63, v226, v198
	v_fmac_f32_e32 v65, v234, v206
	s_waitcnt lgkmcnt(2)
	v_add_f32_e32 v1, v8, v16
	v_fma_f32 v27, v224, v104, 0
	v_fma_f32 v33, v232, v112, 0
	v_fma_f32 v41, v224, v128, 0
	v_fma_f32 v42, v232, v132, 0
	v_fmac_f32_e32 v31, v226, v70
	v_fmac_f32_e32 v26, v234, v78
	v_add_f32_e32 v11, v64, v29
	v_fmac_f32_e32 v25, v227, v51
	v_fmac_f32_e32 v30, v235, v59
	v_add_f32_e32 v19, v62, v55
	v_fmac_f32_e32 v63, v227, v199
	v_fmac_f32_e32 v65, v235, v207
	s_waitcnt lgkmcnt(1)
	v_add_f32_e32 v2, v9, v17
	v_fmac_f32_e32 v27, v225, v105
	v_fmac_f32_e32 v33, v233, v113
	v_fmac_f32_e32 v41, v225, v129
	v_fmac_f32_e32 v42, v233, v133
	v_fmac_f32_e32 v31, v227, v71
	v_fmac_f32_e32 v26, v235, v79
	v_add_f32_e32 v12, v25, v30
	v_add_f32_e32 v20, v63, v65
	v_fmac_f32_e32 v24, v237, v5
	s_waitcnt lgkmcnt(0)
	v_add_f32_e32 v3, v10, v18
	s_nop 1
	v_permlane32_swap_b32_e32 v11, v19
	v_fmac_f32_e32 v27, v222, v106
	v_fmac_f32_e32 v33, v228, v114
	v_fmac_f32_e32 v41, v222, v130
	v_fmac_f32_e32 v42, v228, v134
	v_add_f32_e32 v13, v31, v26
	v_add_f32_e32 v21, v66, v21
	v_fmac_f32_e32 v24, v234, v6
	s_nop 1
	v_permlane32_swap_b32_e32 v12, v20
	v_fmac_f32_e32 v27, v223, v107
	v_fmac_f32_e32 v33, v229, v115
	v_fmac_f32_e32 v41, v223, v131
	v_fmac_f32_e32 v42, v229, v135
	v_fmac_f32_e32 v24, v235, v7
	s_nop 1
	v_permlane32_swap_b32_e32 v13, v21
	v_fmac_f32_e32 v27, v230, v88
	v_fmac_f32_e32 v33, v236, v96
	v_fmac_f32_e32 v41, v230, v108
	v_fmac_f32_e32 v42, v236, v116
	v_fmac_f32_e32 v27, v231, v89
	v_fmac_f32_e32 v33, v237, v97
	v_fmac_f32_e32 v41, v231, v109
	v_fmac_f32_e32 v42, v237, v117
	v_fmac_f32_e32 v27, v226, v90
	v_fmac_f32_e32 v33, v234, v98
	v_fmac_f32_e32 v41, v226, v110
	v_fmac_f32_e32 v42, v234, v118
	v_fmac_f32_e32 v27, v227, v91
	v_fmac_f32_e32 v33, v235, v99
	v_fmac_f32_e32 v41, v227, v111
	v_fmac_f32_e32 v42, v235, v119
	s_waitcnt lgkmcnt(2)
	v_add_f32_e32 v4, v11, v19
	v_add_f32_e32 v14, v27, v33
	v_add_f32_e32 v15, v41, v42
	v_add_f32_e32 v0, v23, v24
	s_waitcnt lgkmcnt(1)
	v_add_f32_e32 v5, v12, v20
	s_waitcnt lgkmcnt(0)
	v_add_f32_e32 v6, v13, v21
	s_nop 1
	v_permlane32_swap_b32_e32 v14, v22
	s_nop 1
	v_permlane32_swap_b32_e32 v15, v0
	s_waitcnt lgkmcnt(1)
	v_add_f32_e32 v7, v14, v22
	s_waitcnt lgkmcnt(0)
	v_add_f32_e32 v0, v15, v0
	s_nop 1
	v_permlane16_swap_b32_e32 v1, v5
	v_permlane16_swap_b32_e32 v2, v6
	v_permlane16_swap_b32_e32 v3, v7
	v_permlane16_swap_b32_e32 v4, v0
	v_add_f32_e32 v1, v1, v5
	v_add_f32_e32 v2, v2, v6
	v_add_f32_e32 v3, v3, v7
	v_add_f32_e32 v0, v4, v0
	v_cndmask_b32_e64 v4, v1, v3, s[12:13]
	v_cndmask_b32_e64 v5, v2, v0, s[12:13]
	v_cndmask_b32_e64 v1, v3, v1, s[12:13]
	v_cndmask_b32_e64 v0, v0, v2, s[12:13]
	s_nop 1
	v_add_f32_dpp v1, v4, v1 row_ror:8 row_mask:0xf bank_mask:0xf
	v_add_f32_dpp v0, v5, v0 row_ror:8 row_mask:0xf bank_mask:0xf
	v_cndmask_b32_e64 v2, v1, v0, s[14:15]
	v_cndmask_b32_e64 v0, v0, v1, s[14:15]
	s_nop 1
	v_mov_b32_dpp v3, v2 row_shl:4 row_mask:0xf bank_mask:0x5
	v_mov_b32_dpp v3, v2 row_shr:4 row_mask:0xf bank_mask:0xa
	s_nop 1
	v_add_f32_e32 v0, v0, v3
	s_nop 1
	v_add_f32_dpp v0, v0, v0 quad_perm:[2,3,0,1] row_mask:0xf bank_mask:0xf
	s_nop 1
	v_add_f32_dpp v0, v0, v0 quad_perm:[1,0,3,2] row_mask:0xf bank_mask:0xf
	s_and_saveexec_b64 s[18:19], s[16:17]
	s_cbranch_execz .LBB0_109
	s_ashr_i32 s44, s36, 8
	s_and_b32 s51, s36, 0xfff
	v_add_f32_e32 v2, v0, v245
	v_mul_f32_e64 v0, |v2|, s50
	v_exp_f32_e32 v3, v0
	v_and_or_b32 v0, s44, -16, v243
	v_ashrrev_i32_e32 v1, 31, v0
	v_lshlrev_b64 v[0:1], 14, v[0:1]
	v_add_f32_e32 v3, 1.0, v3
	v_log_f32_e32 v3, v3
	s_lshl_b32 s44, s51, 2
	v_lshl_add_u64 v[0:1], s[42:43], 0, v[0:1]
	v_min_f32_e32 v2, 0, v2
	v_fmac_f32_e32 v2, 0xbf317218, v3
	v_lshl_add_u64 v[0:1], v[0:1], 0, s[44:45]
	global_store_dword v[0:1], v2, off
	s_branch .LBB0_109
